# v72: cache-policy hint - nt (streaming) on the LN2 final-output f32 stores, which are never re-read
# speedup vs baseline: 1.0075x; 1.0075x over previous
; __device__ __forceinline__ f32x4 unpk4(u32x2 w) { f32x4 r; r.x = bflo(w.x); r.y = bfhi(w.x); r.z = bflo(w.y); r.w = bfhi(w.y); return r; }
; template <int WHICH, int NRW>
; __device__ __forceinline__ void ln_rows(const Params& p, const int row0, const int lane, const f32x4 (&gv)[4], const f32x4 (&bv)[4]) {
;   bf16_t* X1b = (bf16_t*)(p.ws + OFF_X1B);
;   f32x4 v[NRW][4];
; #pragma unroll
;   for (int h = 0; h < NRW; ++h) {
;     const int row = row0 + h;
;     if (row < MP) {
;       const bf16_t* xr = (const bf16_t*)(p.ws + (WHICH == 1 ? OFF_PRE1 : OFF_PRE2)) + (size_t)row * DM;
; #pragma unroll
;       for (int j = 0; j < 4; ++j) v[h][j] = unpk4(*(const u32x2*)(xr + j * 256 + lane * 4));
;     } else {
;       const float* SL = (const float*)(p.ws + (WHICH == 1 ? OFF_SLAB_WO : OFF_SLAB_DN)) + (size_t)(row - MP) * DM;
;       constexpr int NS = (WHICH == 1) ? 8 : 11;
; #pragma unroll
;       for (int j = 0; j < 4; ++j) {
;         f32x4 a;
;         if (WHICH == 1) a = *(const f32x4*)(p.in[1] + (size_t)(row - MP) * DM + j * 256 + lane * 4) * ALPHA_F;
;         else a = unpk4(*(const u32x2*)(X1b + (size_t)row * DM + j * 256 + lane * 4)) * ALPHA_F;
; #pragma unroll
;         for (int q = 0; q < NS; ++q) a += *(const f32x4*)(SL + (size_t)q * MS * DM + j * 256 + lane * 4);
;         v[h][j] = a;
;       }
;     }
;   }
;   float s[NRW], s2[NRW];
; #pragma unroll
;   for (int h = 0; h < NRW; ++h) { s[h] = 0.f;
; #pragma unroll
;     for (int j = 0; j < 4; ++j) s[h] += (v[h][j].x + v[h][j].y) + (v[h][j].z + v[h][j].w); }
; #pragma unroll
;   for (int o = 1; o < 64; o <<= 1) {
; #pragma unroll
;     for (int h = 0; h < NRW; ++h) s[h] += __shfl_xor(s[h], o);
;   }
.Lln2map_keep:
.LBB0_1312:
	v_ashrrev_i32_e32 v193, 31, v192
	v_lshlrev_b64 v[38:39], 11, v[192:193]
	v_lshl_add_u64 v[38:39], v[32:33], 0, v[38:39]
	global_load_dwordx2 v[40:41], v[38:39], off offset:1024
	global_load_dwordx2 v[42:43], v[38:39], off offset:1536
	global_load_dwordx2 v[44:45], v[38:39], off
	global_load_dwordx2 v[46:47], v[38:39], off offset:512
	v_add_u32_e32 v38, 1, v192
	v_ashrrev_i32_e32 v39, 31, v38
	v_lshlrev_b64 v[48:49], 11, v[38:39]
	v_lshl_add_u64 v[48:49], v[32:33], 0, v[48:49]
	global_load_dwordx2 v[50:51], v[48:49], off offset:1024
	global_load_dwordx2 v[64:65], v[48:49], off offset:1536
	global_load_dwordx2 v[66:67], v[48:49], off
	global_load_dwordx2 v[78:79], v[48:49], off offset:512
	v_lshlrev_b64 v[38:39], 12, v[38:39]
	v_add_u32_e32 v77, s66, v77
	s_waitcnt vmcnt(7)
	v_lshlrev_b32_e32 v60, 16, v40
	v_and_b32_e32 v61, 0xffff0000, v40
	s_waitcnt vmcnt(5)
	v_lshlrev_b32_e32 v69, 16, v45
	v_lshlrev_b32_e32 v68, 16, v44
	v_and_b32_e32 v81, 0xffff0000, v45
	v_and_b32_e32 v80, 0xffff0000, v44
	s_waitcnt vmcnt(4)
	v_lshlrev_b32_e32 v71, 16, v47
	v_lshlrev_b32_e32 v70, 16, v46
	v_and_b32_e32 v83, 0xffff0000, v47
	v_and_b32_e32 v82, 0xffff0000, v46
	v_pk_add_f32 v[84:85], v[68:69], v[80:81]
	v_pk_add_f32 v[86:87], v[70:71], v[82:83]
	v_lshlrev_b32_e32 v62, 16, v41
	v_and_b32_e32 v63, 0xffff0000, v41
	v_lshlrev_b32_e32 v59, 16, v42
	v_and_b32_e32 v55, 0xffff0000, v42
	v_add_f32_e32 v42, v84, v85
	v_pk_add_f32 v[84:85], v[86:87], v[86:87] op_sel:[0,1] op_sel_hi:[1,0]
	v_lshlrev_b32_e32 v57, 16, v43
	v_and_b32_e32 v53, 0xffff0000, v43
	v_add_f32_e32 v56, v60, v61
	v_add_f32_e32 v52, v62, v63
	v_add_f32_e32 v58, 0, v42
	v_mov_b32_e32 v85, v55
	s_waitcnt vmcnt(3)
	v_lshlrev_b32_e32 v48, 16, v50
	v_and_b32_e32 v49, 0xffff0000, v50
	v_lshlrev_b32_e32 v50, 16, v51
	v_and_b32_e32 v51, 0xffff0000, v51
	s_waitcnt vmcnt(2)
	v_lshlrev_b32_e32 v47, 16, v64
	v_and_b32_e32 v43, 0xffff0000, v64
	v_lshlrev_b32_e32 v45, 16, v65
	v_and_b32_e32 v41, 0xffff0000, v65
	s_waitcnt vmcnt(1)
	v_lshlrev_b32_e32 v65, 16, v67
	v_lshlrev_b32_e32 v64, 16, v66
	v_and_b32_e32 v89, 0xffff0000, v67
	v_and_b32_e32 v88, 0xffff0000, v66
	s_waitcnt vmcnt(0)
	v_lshlrev_b32_e32 v67, 16, v79
	v_lshlrev_b32_e32 v66, 16, v78
	v_and_b32_e32 v79, 0xffff0000, v79
	v_and_b32_e32 v78, 0xffff0000, v78
	v_pk_add_f32 v[86:87], v[56:57], v[52:53]
	v_pk_add_f32 v[84:85], v[58:59], v[84:85]
	v_pk_add_f32 v[90:91], v[64:65], v[88:89]
	v_pk_add_f32 v[92:93], v[66:67], v[78:79]
	v_add_f32_e32 v44, v48, v49
	v_add_f32_e32 v40, v50, v51
	v_pk_add_f32 v[84:85], v[84:85], v[86:87]
	v_add_f32_e32 v42, v90, v91
	v_pk_add_f32 v[90:91], v[92:93], v[92:93] op_sel:[0,1] op_sel_hi:[1,0]
	v_pk_add_f32 v[92:93], v[44:45], v[40:41]
	v_add_f32_e32 v40, v84, v85
	ds_bpermute_b32 v44, v37, v40
	v_add_f32_e32 v46, 0, v42
	v_mov_b32_e32 v91, v43
	v_pk_add_f32 v[86:87], v[46:47], v[90:91]
	s_waitcnt lgkmcnt(0)
	v_add_f32_e32 v40, v40, v44
	v_pk_add_f32 v[84:85], v[86:87], v[92:93]
	ds_bpermute_b32 v44, v72, v40
	v_add_f32_e32 v42, v84, v85
	ds_bpermute_b32 v46, v37, v42
	s_waitcnt lgkmcnt(1)
	v_add_f32_e32 v40, v40, v44
	ds_bpermute_b32 v44, v73, v40
	s_waitcnt lgkmcnt(1)
	v_add_f32_e32 v42, v42, v46
	ds_bpermute_b32 v46, v72, v42
	s_waitcnt lgkmcnt(1)
	v_add_f32_e32 v40, v40, v44
	ds_bpermute_b32 v44, v74, v40
	s_waitcnt lgkmcnt(1)
	v_add_f32_e32 v42, v42, v46
	ds_bpermute_b32 v46, v73, v42
	s_waitcnt lgkmcnt(1)
	v_add_f32_e32 v40, v40, v44
	ds_bpermute_b32 v44, v75, v40
	s_waitcnt lgkmcnt(1)
	v_add_f32_e32 v42, v42, v46
	ds_bpermute_b32 v46, v74, v42
	s_waitcnt lgkmcnt(1)
	v_add_f32_e32 v40, v40, v44
	ds_bpermute_b32 v44, v76, v40
	s_waitcnt lgkmcnt(1)
	v_add_f32_e32 v42, v42, v46
	ds_bpermute_b32 v46, v75, v42
	s_waitcnt lgkmcnt(1)
	v_add_f32_e32 v44, v40, v44
	v_fmac_f32_e32 v80, 0xba800000, v44
	s_waitcnt lgkmcnt(0)
	v_add_f32_e32 v42, v42, v46
	ds_bpermute_b32 v46, v76, v42
	v_fmac_f32_e32 v81, 0xba800000, v44
	v_fmac_f32_e32 v69, 0xba800000, v44
	v_fmac_f32_e32 v82, 0xba800000, v44
	v_fmac_f32_e32 v83, 0xba800000, v44
	v_fmac_f32_e32 v71, 0xba800000, v44
	v_fmac_f32_e32 v68, 0xba800000, v44
	v_fmac_f32_e32 v70, 0xba800000, v44
	v_mov_b32_e32 v84, v69
	v_mov_b32_e32 v85, v81
	v_mov_b32_e32 v69, v80
	v_mov_b32_e32 v86, v71
	v_mov_b32_e32 v87, v83
	v_mov_b32_e32 v71, v82
	v_pk_mul_f32 v[80:81], v[84:85], v[84:85]
	v_pk_mul_f32 v[82:83], v[68:69], v[68:69]
	v_pk_mul_f32 v[90:91], v[86:87], v[86:87]
	v_pk_mul_f32 v[92:93], v[70:71], v[70:71]
	v_fmac_f32_e32 v60, 0xba800000, v44
	v_fmac_f32_e32 v62, 0xba800000, v44
	v_pk_mov_b32 v[98:99], v[82:83], v[80:81] op_sel:[1,0]
	v_mov_b32_e32 v83, v81
	v_pk_mov_b32 v[80:81], v[92:93], v[90:91] op_sel:[1,0]
	v_mov_b32_e32 v93, v91
	s_waitcnt lgkmcnt(0)
; __device__ __forceinline__ u32x2 pk4(f32x4 v) { u32x2 r; r.x = pk2(v.x, v.y); r.y = pk2(v.z, v.w); return r; }
; template <int WHICH, int NRW>
; __device__ __forceinline__ void ln_rows(const Params& p, const int row0, const int lane, const f32x4 (&gv)[4], const f32x4 (&bv)[4]) {
;     ...
;   for (int h = 0; h < NRW; ++h) { const float mean = s[h] * (1.f / DM); s2[h] = 0.f;
; #pragma unroll
;     for (int j = 0; j < 4; ++j) { v[h][j] = v[h][j] - mean; s2[h] += (v[h][j].x * v[h][j].x + v[h][j].y * v[h][j].y) + (v[h][j].z * v[h][j].z + v[h][j].w * v[h][j].w); } }
; #pragma unroll
;   for (int o = 1; o < 64; o <<= 1) {
; #pragma unroll
;     for (int h = 0; h < NRW; ++h) s2[h] += __shfl_xor(s2[h], o);
;   }
; #pragma unroll
;   for (int h = 0; h < NRW; ++h) {
;     const int row = row0 + h;
;     const float rstd = rsqrtf(s2[h] * (1.f / DM) + LN_EPS_F);
; #pragma unroll
;     for (int j = 0; j < 4; ++j) {
;       const f32x4 o = v[h][j] * rstd * gv[j] + bv[j];
;       if (WHICH == 1) *(u32x2*)(X1b + (size_t)row * DM + j * 256 + lane * 4) = pk4(o);
;       else *(f32x4*)(p.out + (size_t)row * DM + j * 256 + lane * 4) = o;
;     }
;   }
	v_add_f32_e32 v46, v42, v46
	v_fmac_f32_e32 v61, 0xba800000, v44
	v_fmac_f32_e32 v63, 0xba800000, v44
	v_mul_f32_e32 v40, v60, v60
	v_mul_f32_e32 v42, v62, v62
	v_pk_add_f32 v[82:83], v[98:99], v[82:83]
	v_pk_add_f32 v[80:81], v[80:81], v[92:93]
	v_fmac_f32_e32 v53, 0xba800000, v44
	v_fmac_f32_e32 v57, 0xba800000, v44
	v_fmac_f32_e32 v55, 0xba800000, v44
	v_pk_fma_f32 v[94:95], v[60:61], v[60:61], v[40:41] op_sel_hi:[1,1,0]
	v_pk_fma_f32 v[96:97], v[62:63], v[62:63], v[42:43] op_sel_hi:[1,1,0]
	v_pk_add_f32 v[82:83], v[82:83], v[82:83] op_sel_hi:[0,1]
	v_pk_add_f32 v[80:81], v[80:81], v[80:81] op_sel_hi:[0,1]
	v_fmac_f32_e32 v59, 0xba800000, v44
	v_mul_f32_e32 v94, v59, v59
	v_mul_f32_e32 v96, v55, v55
	v_mul_f32_e32 v82, v57, v57
	v_mul_f32_e32 v80, v53, v53
	v_fmac_f32_e32 v88, 0xba800000, v46
	v_fmac_f32_e32 v89, 0xba800000, v46
	v_fmac_f32_e32 v65, 0xba800000, v46
	v_pk_add_f32 v[90:91], v[94:95], v[96:97]
	v_pk_add_f32 v[80:81], v[82:83], v[80:81]
	v_fmac_f32_e32 v64, 0xba800000, v46
	v_mov_b32_e32 v82, v65
	v_mov_b32_e32 v83, v89
	v_mov_b32_e32 v65, v88
	v_pk_add_f32 v[80:81], v[90:91], v[80:81]
	v_pk_mul_f32 v[90:91], v[82:83], v[82:83]
	v_pk_mul_f32 v[88:89], v[64:65], v[64:65]
	v_fmac_f32_e32 v78, 0xba800000, v46
	v_fmac_f32_e32 v79, 0xba800000, v46
	v_fmac_f32_e32 v67, 0xba800000, v46
	v_pk_mov_b32 v[92:93], v[88:89], v[90:91] op_sel:[1,0]
	v_mov_b32_e32 v89, v91
	v_fmac_f32_e32 v66, 0xba800000, v46
	v_mov_b32_e32 v90, v67
	v_mov_b32_e32 v91, v79
	v_mov_b32_e32 v67, v78
	v_pk_add_f32 v[88:89], v[92:93], v[88:89]
	v_pk_mul_f32 v[92:93], v[90:91], v[90:91]
	v_pk_mul_f32 v[78:79], v[66:67], v[66:67]
	v_fmac_f32_e32 v48, 0xba800000, v46
	v_pk_mov_b32 v[94:95], v[78:79], v[92:93] op_sel:[1,0]
	v_mov_b32_e32 v79, v93
	v_fmac_f32_e32 v49, 0xba800000, v46
	v_fmac_f32_e32 v50, 0xba800000, v46
	v_mul_f32_e32 v40, v48, v48
	v_pk_add_f32 v[78:79], v[94:95], v[78:79]
	v_fmac_f32_e32 v51, 0xba800000, v46
	v_pk_fma_f32 v[92:93], v[48:49], v[48:49], v[40:41] op_sel_hi:[1,1,0]
	v_mul_f32_e32 v40, v50, v50
	v_pk_add_f32 v[88:89], v[88:89], v[88:89] op_sel_hi:[0,1]
	v_pk_add_f32 v[78:79], v[78:79], v[78:79] op_sel_hi:[0,1]
	v_pk_fma_f32 v[94:95], v[50:51], v[50:51], v[40:41] op_sel_hi:[1,1,0]
	v_fmac_f32_e32 v41, 0xba800000, v46
	v_fmac_f32_e32 v45, 0xba800000, v46
	v_fmac_f32_e32 v43, 0xba800000, v46
	v_fmac_f32_e32 v47, 0xba800000, v46
	v_mul_f32_e32 v92, v47, v47
	v_mul_f32_e32 v94, v43, v43
	v_mul_f32_e32 v88, v45, v45
	v_mul_f32_e32 v78, v41, v41
	v_pk_add_f32 v[92:93], v[92:93], v[94:95]
	v_pk_add_f32 v[78:79], v[88:89], v[78:79]
	v_mov_b32_e32 v89, v80
	v_pk_add_f32 v[78:79], v[92:93], v[78:79]
	v_mov_b32_e32 v54, v59
	v_mov_b32_e32 v88, v78
	v_mov_b32_e32 v80, v79
	v_pk_add_f32 v[78:79], v[88:89], v[80:81]
	ds_bpermute_b32 v81, v37, v79
	ds_bpermute_b32 v80, v37, v78
	v_mov_b32_e32 v52, v57
	v_lshl_add_u64 v[56:57], v[34:35], 0, v[38:39]
	s_waitcnt lgkmcnt(0)
	v_pk_add_f32 v[78:79], v[78:79], v[80:81]
	ds_bpermute_b32 v81, v72, v79
	ds_bpermute_b32 v80, v72, v78
	s_waitcnt lgkmcnt(0)
	v_pk_add_f32 v[78:79], v[78:79], v[80:81]
	ds_bpermute_b32 v81, v73, v79
	ds_bpermute_b32 v80, v73, v78
	s_waitcnt lgkmcnt(0)
	v_pk_add_f32 v[78:79], v[78:79], v[80:81]
	ds_bpermute_b32 v81, v74, v79
	ds_bpermute_b32 v80, v74, v78
	s_waitcnt lgkmcnt(0)
	v_pk_add_f32 v[78:79], v[78:79], v[80:81]
	ds_bpermute_b32 v81, v75, v79
	ds_bpermute_b32 v80, v75, v78
	s_waitcnt lgkmcnt(0)
	v_pk_add_f32 v[78:79], v[78:79], v[80:81]
	ds_bpermute_b32 v81, v76, v79
	ds_bpermute_b32 v80, v76, v78
	s_waitcnt lgkmcnt(0)
	v_pk_add_f32 v[78:79], v[78:79], v[80:81]
	s_nop 0
	v_pk_fma_f32 v[88:89], v[78:79], s[6:7], v[36:37] op_sel_hi:[1,0,0]
	v_lshlrev_b64 v[78:79], 12, v[192:193]
	v_mul_f32_e32 v40, 0x4b800000, v89
	v_cmp_gt_f32_e32 vcc, s8, v89
	v_lshl_add_u64 v[92:93], v[34:35], 0, v[78:79]
	v_add_u32_e32 v192, s7, v192
	v_cndmask_b32_e32 v40, v89, v40, vcc
	v_rsq_f32_e32 v40, v40
	s_nop 0
	v_mul_f32_e32 v42, 0x45800000, v40
	v_cndmask_b32_e32 v40, v40, v42, vcc
	v_pk_mul_f32 v[68:69], v[68:69], v[40:41] op_sel_hi:[1,0]
	v_pk_mul_f32 v[78:79], v[84:85], v[40:41] op_sel_hi:[1,0]
	v_pk_mul_f32 v[60:61], v[60:61], v[40:41] op_sel_hi:[1,0]
	v_pk_fma_f32 v[80:81], v[2:3], v[78:79], v[6:7]
	v_pk_fma_f32 v[78:79], v[0:1], v[68:69], v[4:5]
	v_pk_mul_f32 v[68:69], v[70:71], v[40:41] op_sel_hi:[1,0]
	v_pk_mul_f32 v[70:71], v[86:87], v[40:41] op_sel_hi:[1,0]
	v_pk_mul_f32 v[62:63], v[62:63], v[40:41] op_sel_hi:[1,0]
	v_pk_mul_f32 v[58:59], v[54:55], v[40:41] op_sel_hi:[1,0]
	v_pk_mul_f32 v[52:53], v[52:53], v[40:41] op_sel_hi:[1,0]
	v_mul_f32_e32 v40, 0x4b800000, v88
	v_cmp_gt_f32_e32 vcc, s8, v88
	v_pk_fma_f32 v[54:55], v[26:27], v[52:53], v[30:31]
	v_pk_fma_f32 v[52:53], v[24:25], v[58:59], v[28:29]
	v_cndmask_b32_e32 v40, v88, v40, vcc
	v_rsq_f32_e32 v40, v40
	global_store_dwordx4 v[92:93], v[52:55], off offset:3072 nt
	v_pk_fma_f32 v[70:71], v[10:11], v[70:71], v[14:15]
	v_pk_fma_f32 v[68:69], v[8:9], v[68:69], v[12:13]
	v_mul_f32_e32 v42, 0x45800000, v40
	v_cndmask_b32_e32 v44, v40, v42, vcc
	v_pk_mul_f32 v[52:53], v[64:65], v[44:45] op_sel_hi:[1,0]
	v_pk_mul_f32 v[54:55], v[82:83], v[44:45] op_sel_hi:[1,0]
	v_pk_fma_f32 v[52:53], v[0:1], v[52:53], v[4:5]
	v_pk_fma_f32 v[54:55], v[2:3], v[54:55], v[6:7]
	global_store_dwordx4 v[56:57], v[52:55], off nt
	v_pk_mul_f32 v[38:39], v[66:67], v[44:45] op_sel_hi:[1,0]
	v_mov_b32_e32 v42, v47
	v_pk_mul_f32 v[52:53], v[90:91], v[44:45] op_sel_hi:[1,0]
	v_mov_b32_e32 v40, v45
	v_pk_fma_f32 v[54:55], v[10:11], v[52:53], v[14:15]
	v_pk_fma_f32 v[52:53], v[8:9], v[38:39], v[12:13]
	v_pk_mul_f32 v[38:39], v[48:49], v[44:45] op_sel_hi:[1,0]
	v_pk_mul_f32 v[48:49], v[50:51], v[44:45] op_sel_hi:[1,0]
	v_pk_mul_f32 v[40:41], v[40:41], v[44:45] op_sel_hi:[1,0]
	v_pk_fma_f32 v[50:51], v[18:19], v[48:49], v[22:23]
	v_pk_fma_f32 v[48:49], v[16:17], v[38:39], v[20:21]
	v_pk_mul_f32 v[38:39], v[42:43], v[44:45] op_sel_hi:[1,0]
	v_cmp_lt_i32_e32 vcc, s9, v77
	v_pk_fma_f32 v[62:63], v[18:19], v[62:63], v[22:23]
	v_pk_fma_f32 v[60:61], v[16:17], v[60:61], v[20:21]
	v_pk_fma_f32 v[40:41], v[26:27], v[40:41], v[30:31]
	v_pk_fma_f32 v[38:39], v[24:25], v[38:39], v[28:29]
	s_or_b64 s[4:5], vcc, s[4:5]
	global_store_dwordx4 v[92:93], v[78:81], off nt
	global_store_dwordx4 v[92:93], v[68:71], off offset:1024 nt
	global_store_dwordx4 v[92:93], v[60:63], off offset:2048 nt
	global_store_dwordx4 v[56:57], v[52:55], off offset:1024 nt
	global_store_dwordx4 v[56:57], v[48:51], off offset:2048 nt
	global_store_dwordx4 v[56:57], v[38:41], off offset:3072 nt
	s_andn2_b64 exec, exec, s[4:5]
	s_cbranch_execnz .LBB0_1312

; __device__ __forceinline__ u32x2 pk4(f32x4 v) { u32x2 r; r.x = pk2(v.x, v.y); r.y = pk2(v.z, v.w); return r; }
; template <int WHICH, int NRW>
; __device__ __forceinline__ void ln_rows(const Params& p, const int row0, const int lane, const f32x4 (&gv)[4], const f32x4 (&bv)[4]) {
;     ...
;   float s[NRW], s2[NRW];
; #pragma unroll
;   for (int h = 0; h < NRW; ++h) { s[h] = 0.f;
; #pragma unroll
;     for (int j = 0; j < 4; ++j) s[h] += (v[h][j].x + v[h][j].y) + (v[h][j].z + v[h][j].w); }
; #pragma unroll
;   for (int o = 1; o < 64; o <<= 1) {
; #pragma unroll
;     for (int h = 0; h < NRW; ++h) s[h] += __shfl_xor(s[h], o);
;   }
; #pragma unroll
;   for (int h = 0; h < NRW; ++h) { const float mean = s[h] * (1.f / DM); s2[h] = 0.f;
; #pragma unroll
;     for (int j = 0; j < 4; ++j) { v[h][j] = v[h][j] - mean; s2[h] += (v[h][j].x * v[h][j].x + v[h][j].y * v[h][j].y) + (v[h][j].z * v[h][j].z + v[h][j].w * v[h][j].w); } }
; #pragma unroll
;   for (int o = 1; o < 64; o <<= 1) {
; #pragma unroll
;     for (int h = 0; h < NRW; ++h) s2[h] += __shfl_xor(s2[h], o);
;   }
; #pragma unroll
;   for (int h = 0; h < NRW; ++h) {
;     const int row = row0 + h;
;     const float rstd = rsqrtf(s2[h] * (1.f / DM) + LN_EPS_F);
; #pragma unroll
;     for (int j = 0; j < 4; ++j) {
;       const f32x4 o = v[h][j] * rstd * gv[j] + bv[j];
;       if (WHICH == 1) *(u32x2*)(X1b + (size_t)row * DM + j * 256 + lane * 4) = pk4(o);
;       else *(f32x4*)(p.out + (size_t)row * DM + j * 256 + lane * 4) = o;
;     }
;   }
.LBB0_1315:
	s_or_b64 exec, exec, s[10:11]
	v_pk_add_f32 v[68:69], v[58:59], v[54:55]
	v_add_f32_e32 v43, v48, v49
	v_add_f32_e32 v41, v68, v69
	v_pk_add_f32 v[68:69], v[56:57], v[52:53]
	v_add_f32_e32 v47, 0, v41
	v_pk_add_f32 v[68:69], v[68:69], v[68:69] op_sel_hi:[0,1]
	v_add_f32_e32 v51, v44, v45
	v_mov_b32_e32 v41, v69
	v_pk_add_f32 v[70:71], v[42:43], v[50:51]
	v_pk_add_f32 v[68:69], v[40:41], v[46:47]
	v_add_u32_e32 v182, s66, v182
	v_pk_add_f32 v[68:69], v[70:71], v[68:69]
	v_lshl_add_u64 v[36:37], v[36:37], 0, s[0:1]
	v_add_f32_e32 v41, v68, v69
	ds_bpermute_b32 v43, v60, v41
	s_waitcnt lgkmcnt(0)
	v_add_f32_e32 v41, v41, v43
	ds_bpermute_b32 v43, v61, v41
	s_waitcnt lgkmcnt(0)
	v_add_f32_e32 v41, v41, v43
	ds_bpermute_b32 v43, v62, v41
	s_waitcnt lgkmcnt(0)
	v_add_f32_e32 v41, v41, v43
	ds_bpermute_b32 v43, v63, v41
	s_waitcnt lgkmcnt(0)
	v_add_f32_e32 v41, v41, v43
	ds_bpermute_b32 v43, v64, v41
	s_waitcnt lgkmcnt(0)
	v_add_f32_e32 v41, v41, v43
	ds_bpermute_b32 v43, v65, v41
	s_waitcnt lgkmcnt(0)
	v_add_f32_e32 v41, v41, v43
	v_fmac_f32_e32 v58, 0xba800000, v41
	v_fmac_f32_e32 v55, 0xba800000, v41
	v_fmac_f32_e32 v59, 0xba800000, v41
	v_fmac_f32_e32 v56, 0xba800000, v41
	v_fmac_f32_e32 v53, 0xba800000, v41
	v_fmac_f32_e32 v57, 0xba800000, v41
	v_fmac_f32_e32 v54, 0xba800000, v41
	v_fmac_f32_e32 v52, 0xba800000, v41
	v_mov_b32_e32 v68, v59
	v_mov_b32_e32 v69, v55
	v_mov_b32_e32 v55, v58
	v_mov_b32_e32 v58, v57
	v_mov_b32_e32 v59, v53
	v_mov_b32_e32 v53, v56
	v_pk_mul_f32 v[56:57], v[68:69], v[68:69]
	v_pk_mul_f32 v[70:71], v[54:55], v[54:55]
	v_pk_mul_f32 v[72:73], v[58:59], v[58:59]
	v_pk_mul_f32 v[74:75], v[52:53], v[52:53]
	v_pk_mov_b32 v[76:77], v[70:71], v[56:57] op_sel:[1,0]
	v_mov_b32_e32 v71, v57
	v_pk_mov_b32 v[56:57], v[74:75], v[72:73] op_sel:[1,0]
	v_mov_b32_e32 v75, v73
	v_pk_add_f32 v[56:57], v[56:57], v[74:75]
	v_fmac_f32_e32 v48, 0xba800000, v41
	v_pk_add_f32 v[56:57], v[56:57], v[56:57] op_sel_hi:[0,1]
	v_fmac_f32_e32 v49, 0xba800000, v41
	v_fmac_f32_e32 v44, 0xba800000, v41
	v_mul_f32_e32 v56, v48, v48
	v_pk_add_f32 v[70:71], v[76:77], v[70:71]
	v_fmac_f32_e32 v45, 0xba800000, v41
	v_pk_fma_f32 v[72:73], v[48:49], v[48:49], v[56:57] op_sel_hi:[1,1,0]
	v_mul_f32_e32 v56, v44, v44
	v_pk_add_f32 v[70:71], v[70:71], v[70:71] op_sel_hi:[0,1]
	v_pk_fma_f32 v[74:75], v[44:45], v[44:45], v[56:57] op_sel_hi:[1,1,0]
	v_fmac_f32_e32 v46, 0xba800000, v41
	v_fmac_f32_e32 v40, 0xba800000, v41
	v_fmac_f32_e32 v50, 0xba800000, v41
	v_fmac_f32_e32 v42, 0xba800000, v41
	v_mul_f32_e32 v72, v42, v42
	v_mul_f32_e32 v74, v50, v50
	v_mul_f32_e32 v70, v40, v40
	v_mul_f32_e32 v56, v46, v46
	v_pk_add_f32 v[72:73], v[72:73], v[74:75]
	v_pk_add_f32 v[56:57], v[70:71], v[56:57]
	s_nop 0
	v_pk_add_f32 v[56:57], v[72:73], v[56:57]
	s_nop 0
	v_add_f32_e32 v41, v56, v57
	ds_bpermute_b32 v43, v60, v41
	s_waitcnt lgkmcnt(0)
	v_add_f32_e32 v41, v41, v43
	ds_bpermute_b32 v43, v61, v41
	s_waitcnt lgkmcnt(0)
	v_add_f32_e32 v41, v41, v43
	ds_bpermute_b32 v43, v62, v41
	s_waitcnt lgkmcnt(0)
	v_add_f32_e32 v41, v41, v43
	ds_bpermute_b32 v43, v63, v41
	s_waitcnt lgkmcnt(0)
	v_add_f32_e32 v41, v41, v43
	ds_bpermute_b32 v43, v64, v41
	s_waitcnt lgkmcnt(0)
	v_add_f32_e32 v41, v41, v43
	ds_bpermute_b32 v43, v65, v41
	s_waitcnt lgkmcnt(0)
	v_add_f32_e32 v41, v41, v43
	v_fmamk_f32 v41, v41, 0x3a800000, v66
	v_mul_f32_e32 v43, 0x4b800000, v41
	v_cmp_gt_f32_e32 vcc, s12, v41
	s_nop 1
	v_cndmask_b32_e32 v41, v41, v43, vcc
	v_rsq_f32_e32 v41, v41
	s_nop 0
	v_mul_f32_e32 v43, 0x45800000, v41
	v_cndmask_b32_e32 v70, v41, v43, vcc
	v_pk_mul_f32 v[56:57], v[54:55], v[70:71] op_sel_hi:[1,0]
	v_pk_mul_f32 v[54:55], v[68:69], v[70:71] op_sel_hi:[1,0]
	v_pk_mul_f32 v[68:69], v[52:53], v[70:71] op_sel_hi:[1,0]
	v_pk_mul_f32 v[58:59], v[58:59], v[70:71] op_sel_hi:[1,0]
	s_waitcnt vmcnt(6)
	v_pk_fma_f32 v[54:55], v[2:3], v[54:55], v[6:7]
	v_pk_fma_f32 v[52:53], v[0:1], v[56:57], v[4:5]
	v_pk_mul_f32 v[44:45], v[44:45], v[70:71] op_sel_hi:[1,0]
	v_mov_b32_e32 v43, v50
	v_mov_b32_e32 v41, v46
	s_waitcnt vmcnt(4)
	v_pk_fma_f32 v[58:59], v[10:11], v[58:59], v[14:15]
	v_pk_fma_f32 v[56:57], v[8:9], v[68:69], v[12:13]
	global_store_dwordx4 v[38:39], v[52:55], off nt
	global_store_dwordx4 v[38:39], v[56:59], off offset:1024 nt
	v_pk_mul_f32 v[40:41], v[40:41], v[70:71] op_sel_hi:[1,0]
	s_waitcnt vmcnt(4)
	v_pk_fma_f32 v[54:55], v[18:19], v[44:45], v[22:23]
	v_pk_mul_f32 v[44:45], v[42:43], v[70:71] op_sel_hi:[1,0]
	s_waitcnt vmcnt(2)
	v_pk_fma_f32 v[42:43], v[26:27], v[40:41], v[30:31]
	v_pk_fma_f32 v[40:41], v[24:25], v[44:45], v[28:29]
	v_pk_mul_f32 v[48:49], v[48:49], v[70:71] op_sel_hi:[1,0]
	global_store_dwordx4 v[38:39], v[40:43], off offset:3072 nt
	v_pk_fma_f32 v[52:53], v[16:17], v[48:49], v[20:21]
	global_store_dwordx4 v[38:39], v[52:55], off offset:2048 nt
	v_add_u32_e32 v40, 0x4000, v182
	v_cmp_lt_i32_e32 vcc, s13, v40
	s_or_b64 s[6:7], vcc, s[6:7]
	v_lshl_add_u64 v[38:39], v[38:39], 0, s[4:5]
	s_andn2_b64 exec, exec, s[6:7]
	s_cbranch_execz .LBB0_1320
